# retention waves 4-7 post-B2: inner-block LDS reads issued before the state publish, tail rewritten (packed sum of squares, address math in MFMA shadow, no exec ladder), on v49
# baseline (speedup 1.0000x reference)
; #define LAS __attribute__((address_space(3)))
; __device__ __forceinline__ void ret_mfma(const Params& P, LAS unsigned char* lds, int wave) {
;     ...
;         const float gam = 1.f - exp2f(-5.f - (float)hh), lg = log2f(gam), g64 = exp2f(lg * 64.f);
;         for (int i = t; i < 33792 / 16; i += NTHREADS) *(LAS u32x4*)(lds + ST_OFF + i * 16) = (u32x4){0u, 0u, 0u, 0u};
;         f32x16 st[2];
; #pragma unroll
;         for (int a = 0; a < 2; ++a)
; #pragma unroll
;             for (int i = 0; i < 16; ++i) st[a][i] = 0.f;
;         const size_t rb = (size_t)b * SEQ;
;         float dec[16];
;         { const int mblk = (wave & 3) >> 1, nblk = wave & 1, n = nblk * 32 + q32;
; #pragma unroll
;           for (int i = 0; i < 16; ++i) { const int mm = mblk * 32 + 8 * (i >> 2) + 4 * hf + (i & 3); const int dist = n > mm ? n - mm : mm - n;
;               dec[i] = wave < 4 ? __builtin_amdgcn_exp2f(lg * (float)(dist - (63 - mm))) : __builtin_amdgcn_exp2f(lg * (float)(n + 1)); } }
;         u32x4 pq[4], pkk[4], pvv;
;         const int vr = t >> 3, vc = t & 7;
; #pragma unroll
;         for (int i = 0; i < 4; ++i) { const int id = t + 512 * i, r = id >> 5, ch = id & 31;
;             pq[i] = *(const u32x4*)(QK + (rb + r) * 2048 + hh * 256 + ch * 8); pkk[i] = *(const u32x4*)(QK + (rb + r) * 2048 + 1024 + hh * 256 + ch * 8); }
;         pvv = *(const u32x4*)(V + (rb + vr) * 2048 + hh * 512 + slice * 64 + vc * 8);
; #pragma unroll 1
;         for (int c = 0; c < 64; ++c) {
; #pragma unroll
;             for (int i = 0; i < 4; ++i) { const int id = t + 512 * i, r = id >> 5, ch = id & 31;
;                 *(LAS u32x4*)(lds + Q_OFF + r * QP + ch * 16) = pq[i]; *(LAS u32x4*)(lds + K_OFF + r * QP + ch * 16) = pkk[i]; }
;             *(LAS u32x4*)(lds + V_OFF + vr * VP + vc * 16) = pvv;
;             __syncthreads();
;             if (c + 1 < 64) { const size_t r1 = rb + (size_t)(c + 1) * 64;
; #pragma unroll
;                 for (int i = 0; i < 4; ++i) { const int id = t + 512 * i, r = id >> 5, ch = id & 31;
;                     pq[i] = *(const u32x4*)(QK + (r1 + r) * 2048 + hh * 256 + ch * 8); pkk[i] = *(const u32x4*)(QK + (r1 + r) * 2048 + 1024 + hh * 256 + ch * 8); }
;                 pvv = *(const u32x4*)(V + (r1 + vr) * 2048 + hh * 512 + slice * 64 + vc * 8); }
.LBB0_252:
	s_or_b64 exec, exec, s[8:9]
	s_ashr_i32 s9, s28, 6
	s_and_b32 s23, s9, 3
	v_cvt_f32_ubyte0_e32 v0, s23
	v_sub_f32_e32 v0, 0xc0a00000, v0
	v_cmp_gt_f32_e32 vcc, s25, v0
	s_lshl_b32 s8, s28, 2
	s_and_b32 s8, s8, 28
	v_cndmask_b32_e32 v1, 0, v182, vcc
	v_add_f32_e32 v0, v0, v1
	s_add_i32 s8, s8, s9
	v_exp_f32_e32 v0, v0
	s_bfe_u32 s22, s28, 0x30003
	s_ashr_i32 s8, s8, 2
	s_and_b64 s[18:19], vcc, exec
	s_cselect_b32 s9, 0xffffffc0, 0
	v_ldexp_f32 v0, v0, s9
	v_sub_f32_e32 v0, 1.0, v0
	v_cmp_gt_f32_e32 vcc, s26, v0
	s_and_b64 s[18:19], vcc, exec
	s_cselect_b32 s9, 32, 0
	v_ldexp_f32 v0, v0, s9
	v_log_f32_e32 v2, v0
	v_cndmask_b32_e32 v1, 0, v183, vcc
	s_mov_b32 s21, s15
	v_mov_b32_e32 v103, v91
	v_sub_f32_e32 v1, v2, v1
	v_mul_f32_e32 v2, 0x42800000, v1
	v_cmp_gt_f32_e32 vcc, s25, v2
	s_and_b64 s[18:19], vcc, exec
	s_cselect_b32 s9, 0xffffffc0, 0
	v_cndmask_b32_e32 v2, 0, v182, vcc
	v_fmac_f32_e32 v2, 0x42800000, v1
	v_exp_f32_e32 v2, v2
	v_mul_f32_e32 v3, v1, v85
	v_mul_f32_e32 v4, v1, v152
	v_exp_f32_e32 v3, v3
	v_ldexp_f32 v106, v2, s9
	v_mul_f32_e32 v2, v1, v153
	v_exp_f32_e32 v105, v2
	v_mul_f32_e32 v2, v1, v154
	v_exp_f32_e32 v110, v2
	v_mul_f32_e32 v2, v1, v155
	v_exp_f32_e32 v111, v2
	v_mul_f32_e32 v2, v1, v156
	v_exp_f32_e32 v104, v4
	v_exp_f32_e32 v112, v2
	v_mul_f32_e32 v2, v1, v157
	v_exp_f32_e32 v113, v2
	v_mul_f32_e32 v2, v1, v158
	s_ashr_i32 s9, s8, 31
	v_exp_f32_e32 v114, v2
	v_mul_f32_e32 v2, v1, v159
	v_exp_f32_e32 v115, v2
	v_mul_f32_e32 v2, v1, v160
	s_lshl_b64 s[18:19], s[8:9], 12
	v_cndmask_b32_e64 v108, v3, v104, s[4:5]
	v_exp_f32_e32 v116, v2
	v_lshl_add_u64 v[2:3], s[18:19], 0, v[92:93]
	v_lshlrev_b64 v[2:3], 12, v[2:3]
	v_lshl_add_u64 v[2:3], s[44:45], 0, v[2:3]
	s_lshl_b32 s14, s23, 9
	v_lshl_add_u64 v[2:3], v[2:3], 0, s[14:15]
	v_lshl_add_u64 v[2:3], v[2:3], 0, v[90:91]
	s_waitcnt vmcnt(0)
	flat_load_dwordx4 v[48:51], v[2:3]
	flat_load_dwordx4 v[52:55], v[2:3] offset:2048
	v_lshl_add_u64 v[2:3], s[18:19], 0, v[94:95]
	v_lshlrev_b64 v[2:3], 12, v[2:3]
	v_lshl_add_u64 v[2:3], s[44:45], 0, v[2:3]
	v_lshl_add_u64 v[2:3], v[2:3], 0, s[14:15]
	v_lshl_add_u64 v[2:3], v[2:3], 0, v[90:91]
	flat_load_dwordx4 v[56:59], v[2:3]
	flat_load_dwordx4 v[60:63], v[2:3] offset:2048
	v_lshl_add_u64 v[2:3], s[18:19], 0, v[96:97]
	v_lshlrev_b64 v[2:3], 12, v[2:3]
	v_lshl_add_u64 v[2:3], s[44:45], 0, v[2:3]
	v_lshl_add_u64 v[2:3], v[2:3], 0, s[14:15]
	v_lshl_add_u64 v[2:3], v[2:3], 0, v[90:91]
	flat_load_dwordx4 v[64:67], v[2:3]
	flat_load_dwordx4 v[68:71], v[2:3] offset:2048
	v_lshl_add_u64 v[2:3], s[18:19], 0, v[98:99]
	v_lshlrev_b64 v[2:3], 12, v[2:3]
	v_lshl_add_u64 v[2:3], s[44:45], 0, v[2:3]
	v_lshl_add_u64 v[2:3], v[2:3], 0, s[14:15]
	v_lshl_add_u64 v[2:3], v[2:3], 0, v[90:91]
	flat_load_dwordx4 v[72:75], v[2:3]
	flat_load_dwordx4 v[76:79], v[2:3] offset:2048
	v_lshl_add_u64 v[2:3], s[18:19], 0, v[88:89]
	v_lshlrev_b64 v[2:3], 12, v[2:3]
	v_lshl_add_u64 v[2:3], s[36:37], 0, v[2:3]
	s_lshl_b32 s8, s23, 10
	s_mov_b32 s9, s15
	v_lshl_add_u64 v[2:3], v[2:3], 0, s[8:9]
	s_lshl_b32 s20, s22, 7
	v_lshl_add_u64 v[2:3], v[2:3], 0, s[20:21]
	v_lshl_add_u64 v[2:3], v[2:3], 0, v[102:103]
	flat_load_dwordx4 v[80:83], v[2:3]
	s_add_u32 s8, s36, s8
	s_addc_u32 s9, s37, 0
	s_add_u32 s8, s8, s20
	v_mul_f32_e32 v2, v1, v161
	s_addc_u32 s9, s9, 0
	s_lshl_b32 s20, s23, 6
	v_exp_f32_e32 v117, v2
	v_mul_f32_e32 v2, v1, v162
	s_add_u32 s20, s60, s20
	v_exp_f32_e32 v118, v2
	v_mul_f32_e32 v2, v1, v163
	s_addc_u32 s21, s61, 0
	s_lshl_b32 s22, s22, 3
	v_exp_f32_e32 v119, v2
	v_mul_f32_e32 v2, v1, v164
	s_add_u32 s20, s20, s22
	v_exp_f32_e32 v120, v2
	v_mul_f32_e32 v2, v1, v165
	s_addc_u32 s21, s21, 0
	v_exp_f32_e32 v121, v2
	v_mul_f32_e32 v2, v1, v166
	v_mul_f32_e32 v1, v1, v167
	s_add_u32 s20, s20, s16
	v_exp_f32_e32 v122, v2
	v_exp_f32_e32 v123, v1
	s_addc_u32 s21, s21, s17
	v_lshl_add_u64 v[124:125], s[8:9], 0, v[102:103]
	s_mov_b64 s[62:63], s[8:9]
	s_add_u32 s8, s8, s27
	v_mov_b32_e32 v0, 0
	s_addc_u32 s9, s9, 0
	s_mov_b32 s29, 0
	v_mov_b32_e32 v126, v106
	v_mov_b32_e32 v127, v106
	v_lshl_add_u64 v[128:129], v[86:87], 1, s[8:9]
	v_mov_b32_e32 v109, v108
	v_lshl_add_u64 v[144:145], v[100:101], 0, s[14:15]
	s_add_u32 s66, s44, s14
	s_addc_u32 s67, s45, s15
	v_lshl_add_u32 v138, v92, 12, v90
	v_lshl_add_u32 v139, v94, 12, v90
	v_lshl_add_u32 v140, v96, 12, v90
	v_lshl_add_u32 v141, v98, 12, v90
	v_lshl_add_u32 v185, v88, 12, v102
	v_mov_b32_e32 v1, v0
	v_mov_b32_e32 v2, v0
	v_mov_b32_e32 v3, v0
	v_mov_b32_e32 v4, v0
	v_mov_b32_e32 v5, v0
	v_mov_b32_e32 v6, v0
	v_mov_b32_e32 v7, v0
	v_mov_b32_e32 v8, v0
	v_mov_b32_e32 v9, v0
	v_mov_b32_e32 v10, v0
	v_mov_b32_e32 v11, v0
	v_mov_b32_e32 v12, v0
	v_mov_b32_e32 v13, v0
	v_mov_b32_e32 v14, v0
	v_mov_b32_e32 v15, v0
	v_mov_b32_e32 v16, v0
	v_mov_b32_e32 v17, v0
	v_mov_b32_e32 v18, v0
	v_mov_b32_e32 v19, v0
	v_mov_b32_e32 v20, v0
	v_mov_b32_e32 v21, v0
	v_mov_b32_e32 v22, v0
	v_mov_b32_e32 v23, v0
	v_mov_b32_e32 v24, v0
	v_mov_b32_e32 v25, v0
	v_mov_b32_e32 v26, v0
	v_mov_b32_e32 v27, v0
	v_mov_b32_e32 v28, v0
	v_mov_b32_e32 v29, v0
	v_mov_b32_e32 v30, v0
	v_mov_b32_e32 v31, v0
	s_add_u32 s8, s18, 64
	s_addc_u32 s9, s19, 0
	v_lshl_add_u64 v[32:33], s[8:9], 0, v[92:93]
	v_lshlrev_b64 v[32:33], 12, v[32:33]
	v_lshl_add_u64 v[32:33], v[144:145], 0, v[32:33]
	global_load_dwordx4 v[226:229], v[32:33], off
	global_load_dwordx4 v[230:233], v[32:33], off offset:2048
	v_lshl_add_u64 v[32:33], s[8:9], 0, v[94:95]
	v_lshlrev_b64 v[32:33], 12, v[32:33]
	v_lshl_add_u64 v[32:33], v[144:145], 0, v[32:33]
	global_load_dwordx4 v[234:237], v[32:33], off
	global_load_dwordx4 v[238:241], v[32:33], off offset:2048
	v_lshl_add_u64 v[32:33], s[8:9], 0, v[96:97]
	v_lshlrev_b64 v[32:33], 12, v[32:33]
	v_lshl_add_u64 v[32:33], v[144:145], 0, v[32:33]
	global_load_dwordx4 v[246:249], v[32:33], off
	global_load_dwordx4 v[250:253], v[32:33], off offset:2048
	v_lshl_add_u64 v[32:33], s[8:9], 0, v[98:99]
	v_lshlrev_b64 v[32:33], 12, v[32:33]
	v_lshl_add_u64 v[32:33], v[144:145], 0, v[32:33]
	global_load_dwordx4 v[206:209], v[32:33], off
	global_load_dwordx4 v[130:133], v[32:33], off offset:2048
	v_lshl_add_u64 v[32:33], s[8:9], 0, v[88:89]
	v_lshlrev_b64 v[32:33], 12, v[32:33]
	v_lshl_add_u64 v[32:33], v[124:125], 0, v[32:33]
	global_load_dwordx4 v[134:137], v[32:33], off
	s_waitcnt vmcnt(0)
	s_branch .LBB0_255
.LBB0_254:
	s_cmp_eq_u32 s14, 64
	s_mov_b32 s29, s14
	s_waitcnt lgkmcnt(0)
	s_barrier
	s_cbranch_scc1 .LBB0_248

; #define LAS __attribute__((address_space(3)))
; __device__ __forceinline__ unsigned cvt_pk_bf16(float lo, float hi) { f32x2 v = {lo, hi}; bf16x2_t b = __builtin_convertvector(v, bf16x2_t); return __builtin_bit_cast(unsigned, b); }
; __device__ __forceinline__ void ret_mfma(const Params& P, LAS unsigned char* lds, int wave) {
;     ...
; #pragma unroll
;                 for (int vb = 0; vb < 2; ++vb)
; #pragma unroll
;                     for (int i = 0; i < 16; ++i) { const int dv = vb * 32 + 8 * (i >> 2) + 4 * hf + (i & 3);
;                         *(LAS bf16_t*)(lds + ST_OFF + dv * QP + (wave * 32 + q32) * 2) = (bf16_t)(cvt_pk_bf16(st[vb][i], 0.f) & 0xffffu); }
;             }
;             if (wave >= 4) {
;                 const int w4 = wave - 4, dvblk = w4 >> 1, nblk = w4 & 1, n = nblk * 32 + q32;
; #pragma unroll
;                 for (int ks = 0; ks < 4; ++ks) {
;                     const LAS unsigned char* p = lds + V_OFF + (16 * ks + trrow) * VP + dvblk * 64 + trcol;
;                     const bf16x8 a = tr_pair(p, p + 4 * VP);
;                     const bf16x8 bs = *(const LAS bf16x8*)(lds + S_OFF + n * SP + (16 * ks + 8 * hf) * 2);
;                     acc = __builtin_amdgcn_mfma_f32_32x32x16_bf16(a, bs, acc, 0, 0, 0);
;                 }
;                 float sq = 0.f;
; #pragma unroll
;                 for (int i = 0; i < 16; ++i) sq += acc[i] * acc[i];
;                 sq += __shfl_xor(sq, 32);
;                 if (hf == 0) rssq[(r0 + n) * 64 + hh * 16 + slice * 2 + dvblk] = sq;
;                 bf16_t* op = V + (r0 + n) * 2048 + hh * 512 + slice * 64 + dvblk * 32 + 4 * hf;
; #pragma unroll
;                 for (int j = 0; j < 4; ++j) { u32x2 w; w.x = cvt_pk_bf16(acc[4 * j], acc[4 * j + 1]); w.y = cvt_pk_bf16(acc[4 * j + 2], acc[4 * j + 3]); *(u32x2*)(op + 8 * j) = w; }
;             }
.LBB0_265:
	s_waitcnt lgkmcnt(0)
	s_barrier
	s_and_b64 vcc, exec, s[8:9]
	s_cbranch_vccz .Lret_w47
	v_cvt_pk_bf16_f32 v218, v0, v1
	v_cvt_pk_bf16_f32 v219, v2, v3
	ds_write_b64 v242, v[218:219]
	v_cvt_pk_bf16_f32 v220, v4, v5
	v_cvt_pk_bf16_f32 v221, v6, v7
	ds_write_b64 v242, v[220:221] offset:16
	v_cvt_pk_bf16_f32 v222, v8, v9
	v_cvt_pk_bf16_f32 v223, v10, v11
	ds_write_b64 v242, v[222:223] offset:32
	v_cvt_pk_bf16_f32 v224, v12, v13
	v_cvt_pk_bf16_f32 v225, v14, v15
	ds_write_b64 v242, v[224:225] offset:48
	v_cvt_pk_bf16_f32 v218, v16, v17
	v_cvt_pk_bf16_f32 v219, v18, v19
	ds_write_b64 v242, v[218:219] offset:16896
	v_cvt_pk_bf16_f32 v220, v20, v21
	v_cvt_pk_bf16_f32 v221, v22, v23
	ds_write_b64 v242, v[220:221] offset:16912
	v_cvt_pk_bf16_f32 v222, v24, v25
	v_cvt_pk_bf16_f32 v223, v26, v27
	ds_write_b64 v242, v[222:223] offset:16928
	v_cvt_pk_bf16_f32 v224, v28, v29
	v_cvt_pk_bf16_f32 v225, v30, v31
	ds_write_b64 v242, v[224:225] offset:16944
	s_branch .LBB0_254
.Lret_w47:
	ds_read_b64_tr_b16 v[190:191], v181
	ds_read_b64_tr_b16 v[192:193], v181 offset:768
	v_add_u32_e32 v103, v151, v149
	ds_read_b128 v[194:197], v103
	ds_read_b64_tr_b16 v[198:199], v181 offset:3072
	ds_read_b64_tr_b16 v[200:201], v181 offset:3840
	ds_read_b128 v[202:205], v103 offset:32
	v_cvt_pk_bf16_f32 v218, v0, v1
	v_cvt_pk_bf16_f32 v219, v2, v3
	ds_write_b64 v242, v[218:219]
	v_cvt_pk_bf16_f32 v220, v4, v5
	v_cvt_pk_bf16_f32 v221, v6, v7
	ds_write_b64 v242, v[220:221] offset:16
	v_cvt_pk_bf16_f32 v222, v8, v9
	v_cvt_pk_bf16_f32 v223, v10, v11
	ds_write_b64 v242, v[222:223] offset:32
	v_cvt_pk_bf16_f32 v224, v12, v13
	v_cvt_pk_bf16_f32 v225, v14, v15
	ds_write_b64 v242, v[224:225] offset:48
	v_cvt_pk_bf16_f32 v218, v16, v17
	v_cvt_pk_bf16_f32 v219, v18, v19
	ds_write_b64 v242, v[218:219] offset:16896
	v_cvt_pk_bf16_f32 v220, v20, v21
	v_cvt_pk_bf16_f32 v221, v22, v23
	ds_write_b64 v242, v[220:221] offset:16912
	v_cvt_pk_bf16_f32 v222, v24, v25
	v_cvt_pk_bf16_f32 v223, v26, v27
	ds_write_b64 v242, v[222:223] offset:16928
	v_cvt_pk_bf16_f32 v224, v28, v29
	v_cvt_pk_bf16_f32 v225, v30, v31
	ds_write_b64 v242, v[224:225] offset:16944
	s_waitcnt lgkmcnt(8)
	v_mfma_f32_32x32x16_bf16 v[32:47], v[190:193], v[194:197], v[32:47]
	s_lshl_b32 s8, s29, 6
	s_or_b32 s8, s18, s8
	v_or_b32_e32 v146, s8, v84
	v_mfma_f32_32x32x16_bf16 v[32:47], v[198:201], v[202:205], v[32:47]
	ds_read_b64_tr_b16 v[190:191], v181 offset:6144
	ds_read_b64_tr_b16 v[192:193], v181 offset:6912
	ds_read_b128 v[194:197], v103 offset:64
	ds_read_b64_tr_b16 v[198:199], v181 offset:9216
	ds_read_b64_tr_b16 v[200:201], v181 offset:9984
	ds_read_b128 v[202:205], v103 offset:96
	s_waitcnt lgkmcnt(0)
	v_mfma_f32_32x32x16_bf16 v[32:47], v[190:193], v[194:197], v[32:47]
	v_mfma_f32_32x32x16_bf16 v[32:47], v[198:201], v[202:205], v[32:47]
	v_mov_b32_e32 v147, s19
	v_lshlrev_b64 v[210:211], 8, v[146:147]
	v_lshlrev_b64 v[146:147], 12, v[146:147]
	v_lshl_add_u64 v[210:211], s[20:21], 0, v[210:211]
	v_lshl_add_u64 v[146:147], v[128:129], 0, v[146:147]
	v_lshl_add_u64 v[146:147], v[146:147], 0, v[142:143]
	s_nop 5
	v_pk_mul_f32 v[212:213], v[32:33], v[32:33]
	v_pk_mul_f32 v[214:215], v[34:35], v[34:35]
	v_pk_fma_f32 v[212:213], v[36:37], v[36:37], v[212:213]
	v_pk_fma_f32 v[214:215], v[38:39], v[38:39], v[214:215]
	v_pk_fma_f32 v[212:213], v[40:41], v[40:41], v[212:213]
	v_pk_fma_f32 v[214:215], v[42:43], v[42:43], v[214:215]
	v_pk_fma_f32 v[212:213], v[44:45], v[44:45], v[212:213]
	v_pk_fma_f32 v[214:215], v[46:47], v[46:47], v[214:215]
	v_pk_add_f32 v[212:213], v[212:213], v[214:215]
	v_cvt_pk_bf16_f32 v32, v32, v33
	v_cvt_pk_bf16_f32 v33, v34, v35
	v_add_f32_e32 v103, v212, v213
	v_cvt_pk_bf16_f32 v34, v36, v37
	v_mov_b32_e32 v107, v103
	v_cvt_pk_bf16_f32 v35, v38, v39
	v_cvt_pk_bf16_f32 v36, v40, v41
	v_permlane32_swap_b32_e32 v103, v107
	v_cvt_pk_bf16_f32 v37, v42, v43
	v_cvt_pk_bf16_f32 v38, v44, v45
	v_cvt_pk_bf16_f32 v39, v46, v47
	v_add_f32_e32 v103, v103, v107
	v_permlane32_swap_b32_e32 v32, v34
	v_permlane32_swap_b32_e32 v33, v35
	v_permlane32_swap_b32_e32 v36, v38
	v_permlane32_swap_b32_e32 v37, v39
	global_store_dwordx4 v[146:147], v[32:35], off
	global_store_dwordx4 v[146:147], v[36:39], off offset:32
	s_mov_b64 s[8:9], exec
	s_andn2_b64 exec, exec, s[6:7]
	global_store_dword v[210:211], v103, off
	s_mov_b64 exec, s[8:9]
	s_branch .LBB0_254
